# GEMM K loop: last 2 LDS-DMA pieces of the two 6-piece phases issued inside that phase's MFMA block (vmcnt 8->6 there)
# baseline (speedup 1.0000x reference)
; #define PG8_STAGE(bufoff, gbase, voff) do { _Pragma("unroll") for (int _i = 0; _i < 2; ++_i) \
;         __builtin_amdgcn_global_load_lds((const unsigned*)((const char*)(gbase) + (voff)[_i]), (LAS unsigned*)(lds + (bufoff) + ldsw + _i * 8192), 16, 0, 0); } while (0)
; #define PG8_LDA(dst, b, h) do { _Pragma("unroll") for (int m = 0; m < 4; ++m) _Pragma("unroll") for (int k = 0; k < 2; ++k) dst[m][k] = *(const LAS bf16x8*)(lds + PG8_SA(b, h) + aoff + m * 2048 + k * 1024); } while (0)
; #define PG8_LDB(dst, b, h) do { _Pragma("unroll") for (int n = 0; n < 2; ++n) _Pragma("unroll") for (int k = 0; k < 2; ++k) dst[n][k] = *(const LAS bf16x8*)(lds + PG8_SB(b, h) + boff + n * 2048 + k * 1024); } while (0)
; #define PG8_MMA(ai, bj, At, Bt) do { __builtin_amdgcn_s_setprio(1); _Pragma("unroll") for (int m = 0; m < 4; ++m) _Pragma("unroll") for (int n = 0; n < 2; ++n) _Pragma("unroll") for (int k = 0; k < 2; ++k) \
;         acc[ai][bj][m][n] = __builtin_amdgcn_mfma_f32_16x16x32_bf16(Bt[n][k], At[m][k], acc[ai][bj][m][n], 0, 0, 0); __builtin_amdgcn_s_setprio(0); } while (0)
; #define PG8_WAIT_V(n) asm volatile("s_waitcnt vmcnt(" #n ")" ::: "memory")
; #define PG8_WAIT_L(n) asm volatile("s_waitcnt lgkmcnt(" #n ")" ::: "memory")
; #define PG8_BAR __builtin_amdgcn_s_barrier()
; #define PG8_SCHED __builtin_amdgcn_sched_barrier(0)
; DI void gemm_phase(LAS unsigned char* lds, const GemmD g, const int kind, const int l) {
;     ...
;             PG8_LDB(B0, 0, 0); PG8_LDB(B1, 0, 1); PG8_SCHED; PG8_LDA(At, 0, 0); PG8_STAGE(PG8_SA(1, 1), a1 + hstepA, voffA);
;             PG8_WAIT_V(8); PG8_WAIT_L(0); PG8_BAR; PG8_MMA(0, 0, At, B0); PG8_MMA(0, 1, At, B1); PG8_BAR; PG8_SCHED;
;             PG8_LDA(At, 0, 1); PG8_STAGE(PG8_SB(0, 0), b2, voffB); PG8_STAGE(PG8_SB(0, 1), b2 + hstepB, voffB); PG8_STAGE(PG8_SA(0, 0), a2, voffA);
;             PG8_WAIT_V(8); PG8_WAIT_L(0); PG8_BAR; PG8_MMA(1, 0, At, B0); PG8_MMA(1, 1, At, B1); PG8_BAR; PG8_SCHED;
.LBB0_254:
	s_add_i32 s10, s6, 2
	s_add_u32 s11, s4, 0x80
	s_addc_u32 s7, s5, 0
	s_add_i32 s14, 0, 0x10000
	s_cmp_eq_u32 s50, s6
	s_cselect_b32 s7, s75, s7
	s_cselect_b32 s6, s74, s11
	v_add_u32_e32 v24, s14, v214
	s_cselect_b32 s13, s77, s9
	s_cselect_b32 s12, s76, s8
	s_add_i32 s11, 0, 0x14000
	ds_read_b128 v[130:133], v24
	ds_read_b128 v[134:137], v24 offset:1024
	ds_read_b128 v[138:141], v24 offset:2048
	ds_read_b128 v[142:145], v24 offset:3072
	v_add_u32_e32 v24, s11, v214
	ds_read_b128 v[146:149], v24
	ds_read_b128 v[150:153], v24 offset:1024
	ds_read_b128 v[154:157], v24 offset:2048
	ds_read_b128 v[172:175], v24 offset:3072
	v_lshl_add_u64 v[240:241], s[4:5], 0, v[168:169]
	s_add_i32 m0, s67, 0xc000
	ds_read_b128 v[176:179], v215
	ds_read_b128 v[180:183], v215 offset:1024
	ds_read_b128 v[216:219], v215 offset:2048
	ds_read_b128 v[220:223], v215 offset:3072
	ds_read_b128 v[224:227], v215 offset:4096
	ds_read_b128 v[228:231], v215 offset:5120
	ds_read_b128 v[232:235], v215 offset:6144
	ds_read_b128 v[236:239], v215 offset:7168
	global_load_lds_dwordx4 v[240:241], off
	v_lshl_add_u64 v[240:241], s[4:5], 0, v[170:171]
	s_add_i32 m0, s67, 0xe000
	s_nop 0
	global_load_lds_dwordx4 v[240:241], off
	s_waitcnt vmcnt(8)
	s_waitcnt lgkmcnt(0)
	s_barrier
	s_setprio 1
	s_waitcnt lgkmcnt(0)
	v_mfma_f32_16x16x32_bf16 v[126:129], v[130:133], v[176:179], v[126:129]
	v_mfma_f32_16x16x32_bf16 v[122:125], v[138:141], v[176:179], v[122:125]
	v_mfma_f32_16x16x32_bf16 v[110:113], v[130:133], v[216:219], v[110:113]
	v_mfma_f32_16x16x32_bf16 v[106:109], v[138:141], v[216:219], v[106:109]
	v_mfma_f32_16x16x32_bf16 v[94:97], v[130:133], v[224:227], v[94:97]
	v_mfma_f32_16x16x32_bf16 v[90:93], v[138:141], v[224:227], v[90:93]
	v_mfma_f32_16x16x32_bf16 v[78:81], v[130:133], v[232:235], v[78:81]
	v_mfma_f32_16x16x32_bf16 v[74:77], v[138:141], v[232:235], v[74:77]
	v_mfma_f32_16x16x32_bf16 v[126:129], v[134:137], v[180:183], v[126:129]
	v_mfma_f32_16x16x32_bf16 v[122:125], v[142:145], v[180:183], v[122:125]
	v_mfma_f32_16x16x32_bf16 v[110:113], v[134:137], v[220:223], v[110:113]
	v_mfma_f32_16x16x32_bf16 v[106:109], v[142:145], v[220:223], v[106:109]
	v_mfma_f32_16x16x32_bf16 v[94:97], v[134:137], v[228:231], v[94:97]
	v_mfma_f32_16x16x32_bf16 v[90:93], v[142:145], v[228:231], v[90:93]
	v_mfma_f32_16x16x32_bf16 v[78:81], v[134:137], v[236:239], v[78:81]
	v_mfma_f32_16x16x32_bf16 v[74:77], v[142:145], v[236:239], v[74:77]
	s_setprio 0
	s_setprio 1
	v_mfma_f32_16x16x32_bf16 v[118:121], v[146:149], v[176:179], v[118:121]
	v_mfma_f32_16x16x32_bf16 v[114:117], v[154:157], v[176:179], v[114:117]
	v_mfma_f32_16x16x32_bf16 v[102:105], v[146:149], v[216:219], v[102:105]
	v_mfma_f32_16x16x32_bf16 v[98:101], v[154:157], v[216:219], v[98:101]
	v_mfma_f32_16x16x32_bf16 v[86:89], v[146:149], v[224:227], v[86:89]
	v_mfma_f32_16x16x32_bf16 v[82:85], v[154:157], v[224:227], v[82:85]
	v_mfma_f32_16x16x32_bf16 v[70:73], v[146:149], v[232:235], v[70:73]
	v_mfma_f32_16x16x32_bf16 v[66:69], v[154:157], v[232:235], v[66:69]
	v_mfma_f32_16x16x32_bf16 v[118:121], v[150:153], v[180:183], v[118:121]
	v_mfma_f32_16x16x32_bf16 v[114:117], v[172:175], v[180:183], v[114:117]
	v_mfma_f32_16x16x32_bf16 v[102:105], v[150:153], v[220:223], v[102:105]
	v_mfma_f32_16x16x32_bf16 v[98:101], v[172:175], v[220:223], v[98:101]
	v_mfma_f32_16x16x32_bf16 v[86:89], v[150:153], v[228:231], v[86:89]
	v_mfma_f32_16x16x32_bf16 v[82:85], v[172:175], v[228:231], v[82:85]
	v_mfma_f32_16x16x32_bf16 v[70:73], v[150:153], v[236:239], v[70:73]
	v_mfma_f32_16x16x32_bf16 v[66:69], v[172:175], v[236:239], v[66:69]
	s_setprio 0
	s_barrier
	s_add_i32 s14, s14, s66
	v_lshl_add_u64 v[240:241], s[12:13], 0, v[160:161]
	s_mov_b32 m0, s14
	ds_read_b128 v[176:179], v215 offset:16384
	ds_read_b128 v[180:183], v215 offset:17408
	ds_read_b128 v[216:219], v215 offset:18432
	ds_read_b128 v[220:223], v215 offset:19456
	ds_read_b128 v[224:227], v215 offset:20480
	ds_read_b128 v[228:231], v215 offset:21504
	ds_read_b128 v[232:235], v215 offset:22528
	ds_read_b128 v[236:239], v215 offset:23552
	global_load_lds_dwordx4 v[240:241], off
	s_add_i32 m0, s14, 0x2000
	v_lshl_add_u64 v[242:243], s[12:13], 0, v[164:165]
	s_add_u32 s12, s12, s54
	s_addc_u32 s13, s13, s55
	s_add_i32 s11, s11, s66
	global_load_lds_dwordx4 v[242:243], off
	v_lshl_add_u64 v[244:245], s[12:13], 0, v[160:161]
	s_mov_b32 m0, s11
	v_lshl_add_u64 v[246:247], s[12:13], 0, v[164:165]
	global_load_lds_dwordx4 v[244:245], off
	s_add_i32 m0, s11, 0x2000
	v_lshl_add_u64 v[248:249], s[6:7], 0, v[158:159]
	global_load_lds_dwordx4 v[246:247], off
	v_lshl_add_u64 v[250:251], s[6:7], 0, v[162:163]
	s_waitcnt vmcnt(6)
	s_waitcnt lgkmcnt(0)
	s_barrier
; #define PG8_STAGE(bufoff, gbase, voff) do { _Pragma("unroll") for (int _i = 0; _i < 2; ++_i) \
;         __builtin_amdgcn_global_load_lds((const unsigned*)((const char*)(gbase) + (voff)[_i]), (LAS unsigned*)(lds + (bufoff) + ldsw + _i * 8192), 16, 0, 0); } while (0)
; #define PG8_LDA(dst, b, h) do { _Pragma("unroll") for (int m = 0; m < 4; ++m) _Pragma("unroll") for (int k = 0; k < 2; ++k) dst[m][k] = *(const LAS bf16x8*)(lds + PG8_SA(b, h) + aoff + m * 2048 + k * 1024); } while (0)
; #define PG8_LDB(dst, b, h) do { _Pragma("unroll") for (int n = 0; n < 2; ++n) _Pragma("unroll") for (int k = 0; k < 2; ++k) dst[n][k] = *(const LAS bf16x8*)(lds + PG8_SB(b, h) + boff + n * 2048 + k * 1024); } while (0)
; #define PG8_MMA(ai, bj, At, Bt) do { __builtin_amdgcn_s_setprio(1); _Pragma("unroll") for (int m = 0; m < 4; ++m) _Pragma("unroll") for (int n = 0; n < 2; ++n) _Pragma("unroll") for (int k = 0; k < 2; ++k) \
;         acc[ai][bj][m][n] = __builtin_amdgcn_mfma_f32_16x16x32_bf16(Bt[n][k], At[m][k], acc[ai][bj][m][n], 0, 0, 0); __builtin_amdgcn_s_setprio(0); } while (0)
; #define PG8_WAIT_V(n) asm volatile("s_waitcnt vmcnt(" #n ")" ::: "memory")
; #define PG8_WAIT_L(n) asm volatile("s_waitcnt lgkmcnt(" #n ")" ::: "memory")
; #define PG8_BAR __builtin_amdgcn_s_barrier()
; #define PG8_SCHED __builtin_amdgcn_sched_barrier(0)
; DI void gemm_phase(LAS unsigned char* lds, const GemmD g, const int kind, const int l) {
;     ...
;             PG8_LDA(At, 0, 1); PG8_STAGE(PG8_SB(0, 0), b2, voffB); PG8_STAGE(PG8_SB(0, 1), b2 + hstepB, voffB); PG8_STAGE(PG8_SA(0, 0), a2, voffA);
;             PG8_WAIT_V(8); PG8_WAIT_L(0); PG8_BAR; PG8_MMA(1, 0, At, B0); PG8_MMA(1, 1, At, B1); PG8_BAR; PG8_SCHED;
;             PG8_LDB(B0, 1, 0); PG8_LDB(B1, 1, 1); PG8_SCHED; PG8_LDA(At, 1, 0); PG8_STAGE(PG8_SA(0, 1), a2 + hstepA, voffA);
;             PG8_WAIT_V(8); PG8_WAIT_L(0); PG8_BAR; PG8_MMA(0, 0, At, B0); PG8_MMA(0, 1, At, B1); PG8_BAR; PG8_SCHED;
	s_setprio 1
	s_waitcnt lgkmcnt(0)
	v_mfma_f32_16x16x32_bf16 v[62:65], v[130:133], v[176:179], v[62:65]
	v_mfma_f32_16x16x32_bf16 v[58:61], v[138:141], v[176:179], v[58:61]
	v_mfma_f32_16x16x32_bf16 v[46:49], v[130:133], v[216:219], v[46:49]
	v_mfma_f32_16x16x32_bf16 v[42:45], v[138:141], v[216:219], v[42:45]
	s_mov_b32 m0, s67
	v_mfma_f32_16x16x32_bf16 v[30:33], v[130:133], v[224:227], v[30:33]
	v_mfma_f32_16x16x32_bf16 v[26:29], v[138:141], v[224:227], v[26:29]
	v_mfma_f32_16x16x32_bf16 v[12:15], v[130:133], v[232:235], v[12:15]
	v_mfma_f32_16x16x32_bf16 v[8:11], v[138:141], v[232:235], v[8:11]
	global_load_lds_dwordx4 v[248:249], off
	v_mfma_f32_16x16x32_bf16 v[62:65], v[134:137], v[180:183], v[62:65]
	v_mfma_f32_16x16x32_bf16 v[58:61], v[142:145], v[180:183], v[58:61]
	v_mfma_f32_16x16x32_bf16 v[46:49], v[134:137], v[220:223], v[46:49]
	v_mfma_f32_16x16x32_bf16 v[42:45], v[142:145], v[220:223], v[42:45]
	v_mfma_f32_16x16x32_bf16 v[30:33], v[134:137], v[228:231], v[30:33]
	v_mfma_f32_16x16x32_bf16 v[26:29], v[142:145], v[228:231], v[26:29]
	v_mfma_f32_16x16x32_bf16 v[12:15], v[134:137], v[236:239], v[12:15]
	v_mfma_f32_16x16x32_bf16 v[8:11], v[142:145], v[236:239], v[8:11]
	s_setprio 0
	s_setprio 1
	v_mfma_f32_16x16x32_bf16 v[54:57], v[146:149], v[176:179], v[54:57]
	v_mfma_f32_16x16x32_bf16 v[50:53], v[154:157], v[176:179], v[50:53]
	v_mfma_f32_16x16x32_bf16 v[38:41], v[146:149], v[216:219], v[38:41]
	v_mfma_f32_16x16x32_bf16 v[34:37], v[154:157], v[216:219], v[34:37]
	s_mov_b32 m0, s25
	v_mfma_f32_16x16x32_bf16 v[20:23], v[146:149], v[224:227], v[20:23]
	v_mfma_f32_16x16x32_bf16 v[16:19], v[154:157], v[224:227], v[16:19]
	v_mfma_f32_16x16x32_bf16 v[4:7], v[146:149], v[232:235], v[4:7]
	v_mfma_f32_16x16x32_bf16 v[0:3], v[154:157], v[232:235], v[0:3]
	global_load_lds_dwordx4 v[250:251], off
	v_mfma_f32_16x16x32_bf16 v[54:57], v[150:153], v[180:183], v[54:57]
	v_mfma_f32_16x16x32_bf16 v[50:53], v[172:175], v[180:183], v[50:53]
	v_mfma_f32_16x16x32_bf16 v[38:41], v[150:153], v[220:223], v[38:41]
	v_mfma_f32_16x16x32_bf16 v[34:37], v[172:175], v[220:223], v[34:37]
	v_mfma_f32_16x16x32_bf16 v[20:23], v[150:153], v[228:231], v[20:23]
	v_mfma_f32_16x16x32_bf16 v[16:19], v[172:175], v[228:231], v[16:19]
	v_mfma_f32_16x16x32_bf16 v[4:7], v[150:153], v[236:239], v[4:7]
	v_mfma_f32_16x16x32_bf16 v[0:3], v[172:175], v[236:239], v[0:3]
	s_setprio 0
	s_barrier
	s_add_i32 s11, 0, 0x18000
	v_add_u32_e32 v24, s11, v214
	s_add_i32 s12, 0, 0x1c000
	ds_read_b128 v[130:133], v24
	ds_read_b128 v[134:137], v24 offset:1024
	ds_read_b128 v[138:141], v24 offset:2048
	ds_read_b128 v[142:145], v24 offset:3072
	v_add_u32_e32 v24, s12, v214
	ds_read_b128 v[146:149], v24
	ds_read_b128 v[150:153], v24 offset:1024
	ds_read_b128 v[154:157], v24 offset:2048
	ds_read_b128 v[172:175], v24 offset:3072
	s_add_u32 s6, s6, s52
	s_addc_u32 s7, s7, s53
	s_mov_b32 m0, s60
	v_lshl_add_u64 v[252:253], s[6:7], 0, v[158:159]
	ds_read_b128 v[176:179], v215 offset:32768
	ds_read_b128 v[180:183], v215 offset:33792
	ds_read_b128 v[216:219], v215 offset:34816
	ds_read_b128 v[220:223], v215 offset:35840
	ds_read_b128 v[224:227], v215 offset:36864
	ds_read_b128 v[228:231], v215 offset:37888
	ds_read_b128 v[232:235], v215 offset:38912
	ds_read_b128 v[236:239], v215 offset:39936
	global_load_lds_dwordx4 v[252:253], off
	v_lshl_add_u64 v[252:253], s[6:7], 0, v[162:163]
	s_mov_b32 m0, s61
	s_nop 0
	global_load_lds_dwordx4 v[252:253], off
	s_waitcnt vmcnt(8)
	s_waitcnt lgkmcnt(0)
	s_barrier
	s_setprio 1
	s_waitcnt lgkmcnt(0)
	v_mfma_f32_16x16x32_bf16 v[126:129], v[130:133], v[176:179], v[126:129]
	v_mfma_f32_16x16x32_bf16 v[122:125], v[138:141], v[176:179], v[122:125]
	v_mfma_f32_16x16x32_bf16 v[110:113], v[130:133], v[216:219], v[110:113]
	v_mfma_f32_16x16x32_bf16 v[106:109], v[138:141], v[216:219], v[106:109]
	v_mfma_f32_16x16x32_bf16 v[94:97], v[130:133], v[224:227], v[94:97]
	v_mfma_f32_16x16x32_bf16 v[90:93], v[138:141], v[224:227], v[90:93]
	v_mfma_f32_16x16x32_bf16 v[78:81], v[130:133], v[232:235], v[78:81]
	v_mfma_f32_16x16x32_bf16 v[74:77], v[138:141], v[232:235], v[74:77]
	v_mfma_f32_16x16x32_bf16 v[126:129], v[134:137], v[180:183], v[126:129]
	v_mfma_f32_16x16x32_bf16 v[122:125], v[142:145], v[180:183], v[122:125]
	v_mfma_f32_16x16x32_bf16 v[110:113], v[134:137], v[220:223], v[110:113]
	v_mfma_f32_16x16x32_bf16 v[106:109], v[142:145], v[220:223], v[106:109]
	v_mfma_f32_16x16x32_bf16 v[94:97], v[134:137], v[228:231], v[94:97]
	v_mfma_f32_16x16x32_bf16 v[90:93], v[142:145], v[228:231], v[90:93]
	v_mfma_f32_16x16x32_bf16 v[78:81], v[134:137], v[236:239], v[78:81]
	v_mfma_f32_16x16x32_bf16 v[74:77], v[142:145], v[236:239], v[74:77]
	s_setprio 0
	s_setprio 1
	v_mfma_f32_16x16x32_bf16 v[118:121], v[146:149], v[176:179], v[118:121]
	v_mfma_f32_16x16x32_bf16 v[114:117], v[154:157], v[176:179], v[114:117]
	v_mfma_f32_16x16x32_bf16 v[102:105], v[146:149], v[216:219], v[102:105]
	v_mfma_f32_16x16x32_bf16 v[98:101], v[154:157], v[216:219], v[98:101]
	v_mfma_f32_16x16x32_bf16 v[86:89], v[146:149], v[224:227], v[86:89]
	v_mfma_f32_16x16x32_bf16 v[82:85], v[154:157], v[224:227], v[82:85]
	v_mfma_f32_16x16x32_bf16 v[70:73], v[146:149], v[232:235], v[70:73]
	v_mfma_f32_16x16x32_bf16 v[66:69], v[154:157], v[232:235], v[66:69]
	v_mfma_f32_16x16x32_bf16 v[118:121], v[150:153], v[180:183], v[118:121]
	v_mfma_f32_16x16x32_bf16 v[114:117], v[172:175], v[180:183], v[114:117]
	v_mfma_f32_16x16x32_bf16 v[102:105], v[150:153], v[220:223], v[102:105]
	v_mfma_f32_16x16x32_bf16 v[98:101], v[172:175], v[220:223], v[98:101]
	v_mfma_f32_16x16x32_bf16 v[86:89], v[150:153], v[228:231], v[86:89]
	v_mfma_f32_16x16x32_bf16 v[82:85], v[172:175], v[228:231], v[82:85]
	v_mfma_f32_16x16x32_bf16 v[70:73], v[150:153], v[236:239], v[70:73]
	v_mfma_f32_16x16x32_bf16 v[66:69], v[172:175], v[236:239], v[66:69]
	s_setprio 0
	s_barrier
; #define PG8_STAGE(bufoff, gbase, voff) do { _Pragma("unroll") for (int _i = 0; _i < 2; ++_i) \
;         __builtin_amdgcn_global_load_lds((const unsigned*)((const char*)(gbase) + (voff)[_i]), (LAS unsigned*)(lds + (bufoff) + ldsw + _i * 8192), 16, 0, 0); } while (0)
; #define PG8_LDA(dst, b, h) do { _Pragma("unroll") for (int m = 0; m < 4; ++m) _Pragma("unroll") for (int k = 0; k < 2; ++k) dst[m][k] = *(const LAS bf16x8*)(lds + PG8_SA(b, h) + aoff + m * 2048 + k * 1024); } while (0)
; #define PG8_MMA(ai, bj, At, Bt) do { __builtin_amdgcn_s_setprio(1); _Pragma("unroll") for (int m = 0; m < 4; ++m) _Pragma("unroll") for (int n = 0; n < 2; ++n) _Pragma("unroll") for (int k = 0; k < 2; ++k) \
;         acc[ai][bj][m][n] = __builtin_amdgcn_mfma_f32_16x16x32_bf16(Bt[n][k], At[m][k], acc[ai][bj][m][n], 0, 0, 0); __builtin_amdgcn_s_setprio(0); } while (0)
; #define PG8_WAIT_V(n) asm volatile("s_waitcnt vmcnt(" #n ")" ::: "memory")
; #define PG8_WAIT_L(n) asm volatile("s_waitcnt lgkmcnt(" #n ")" ::: "memory")
; #define PG8_BAR __builtin_amdgcn_s_barrier()
; #define PG8_SCHED __builtin_amdgcn_sched_barrier(0)
; DI void gemm_phase(LAS unsigned char* lds, const GemmD g, const int kind, const int l) {
;     ...
;             PG8_LDA(At, 1, 1); PG8_STAGE(PG8_SB(1, 0), b3, voffB); PG8_STAGE(PG8_SB(1, 1), b3 + hstepB, voffB); PG8_STAGE(PG8_SA(1, 0), a3, voffA);
;             PG8_WAIT_V(8); PG8_WAIT_L(0); PG8_BAR; PG8_MMA(1, 0, At, B0); PG8_MMA(1, 1, At, B1); PG8_BAR; PG8_SCHED;
;         }
;         if (wr == 0) PG8_BAR;
;         epilogue(kind, l, acc, cur, wr, wc, fr, fq);
;         __builtin_amdgcn_s_waitcnt(0x0F70);
;         if (!has_next) break;
	s_add_i32 s6, s11, s66
	v_lshl_add_u64 v[240:241], v[240:241], 0, s[80:81]
	s_mov_b32 m0, s6
	ds_read_b128 v[176:179], v215 offset:49152
	ds_read_b128 v[180:183], v215 offset:50176
	ds_read_b128 v[216:219], v215 offset:51200
	ds_read_b128 v[220:223], v215 offset:52224
	ds_read_b128 v[224:227], v215 offset:53248
	ds_read_b128 v[228:231], v215 offset:54272
	ds_read_b128 v[232:235], v215 offset:55296
	ds_read_b128 v[236:239], v215 offset:56320
	global_load_lds_dwordx4 v[240:241], off
	v_lshl_add_u64 v[240:241], v[242:243], 0, s[80:81]
	s_add_i32 m0, s6, 0x2000
	s_add_i32 s6, s12, s66
	global_load_lds_dwordx4 v[240:241], off
	v_lshl_add_u64 v[240:241], v[244:245], 0, s[80:81]
	s_mov_b32 m0, s6
	s_nop 0
	global_load_lds_dwordx4 v[240:241], off
	v_lshl_add_u64 v[240:241], v[246:247], 0, s[80:81]
	s_add_i32 m0, s6, 0x2000
	s_nop 0
	global_load_lds_dwordx4 v[240:241], off
	v_lshl_add_u64 v[248:249], v[248:249], 0, s[80:81]
	v_lshl_add_u64 v[250:251], v[250:251], 0, s[80:81]
	s_waitcnt vmcnt(6)
	s_waitcnt lgkmcnt(0)
	s_barrier
	s_setprio 1
	s_waitcnt lgkmcnt(0)
	v_mfma_f32_16x16x32_bf16 v[62:65], v[130:133], v[176:179], v[62:65]
	v_mfma_f32_16x16x32_bf16 v[58:61], v[138:141], v[176:179], v[58:61]
	v_mfma_f32_16x16x32_bf16 v[46:49], v[130:133], v[216:219], v[46:49]
	v_mfma_f32_16x16x32_bf16 v[42:45], v[138:141], v[216:219], v[42:45]
	s_mov_b32 m0, s2
	v_mfma_f32_16x16x32_bf16 v[30:33], v[130:133], v[224:227], v[30:33]
	v_mfma_f32_16x16x32_bf16 v[26:29], v[138:141], v[224:227], v[26:29]
	v_mfma_f32_16x16x32_bf16 v[12:15], v[130:133], v[232:235], v[12:15]
	v_mfma_f32_16x16x32_bf16 v[8:11], v[138:141], v[232:235], v[8:11]
	global_load_lds_dwordx4 v[248:249], off
	v_mfma_f32_16x16x32_bf16 v[62:65], v[134:137], v[180:183], v[62:65]
	v_mfma_f32_16x16x32_bf16 v[58:61], v[142:145], v[180:183], v[58:61]
	v_mfma_f32_16x16x32_bf16 v[46:49], v[134:137], v[220:223], v[46:49]
	v_mfma_f32_16x16x32_bf16 v[42:45], v[142:145], v[220:223], v[42:45]
	v_mfma_f32_16x16x32_bf16 v[30:33], v[134:137], v[228:231], v[30:33]
	v_mfma_f32_16x16x32_bf16 v[26:29], v[142:145], v[228:231], v[26:29]
	v_mfma_f32_16x16x32_bf16 v[12:15], v[134:137], v[236:239], v[12:15]
	v_mfma_f32_16x16x32_bf16 v[8:11], v[142:145], v[236:239], v[8:11]
	s_setprio 0
	s_setprio 1
	v_mfma_f32_16x16x32_bf16 v[54:57], v[146:149], v[176:179], v[54:57]
	v_mfma_f32_16x16x32_bf16 v[50:53], v[154:157], v[176:179], v[50:53]
	v_mfma_f32_16x16x32_bf16 v[38:41], v[146:149], v[216:219], v[38:41]
	v_mfma_f32_16x16x32_bf16 v[34:37], v[154:157], v[216:219], v[34:37]
	s_mov_b32 m0, s82
	v_mfma_f32_16x16x32_bf16 v[20:23], v[146:149], v[224:227], v[20:23]
	v_mfma_f32_16x16x32_bf16 v[16:19], v[154:157], v[224:227], v[16:19]
	v_mfma_f32_16x16x32_bf16 v[4:7], v[146:149], v[232:235], v[4:7]
	v_mfma_f32_16x16x32_bf16 v[0:3], v[154:157], v[232:235], v[0:3]
	global_load_lds_dwordx4 v[250:251], off
	v_mfma_f32_16x16x32_bf16 v[54:57], v[150:153], v[180:183], v[54:57]
	v_mfma_f32_16x16x32_bf16 v[50:53], v[172:175], v[180:183], v[50:53]
	v_mfma_f32_16x16x32_bf16 v[38:41], v[150:153], v[220:223], v[38:41]
	v_mfma_f32_16x16x32_bf16 v[34:37], v[172:175], v[220:223], v[34:37]
	v_mfma_f32_16x16x32_bf16 v[20:23], v[150:153], v[228:231], v[20:23]
	v_mfma_f32_16x16x32_bf16 v[16:19], v[172:175], v[228:231], v[16:19]
	v_mfma_f32_16x16x32_bf16 v[4:7], v[150:153], v[236:239], v[4:7]
	v_mfma_f32_16x16x32_bf16 v[0:3], v[172:175], v[236:239], v[0:3]
	s_setprio 0
	s_barrier
	s_add_u32 s4, s4, 0x100
	s_addc_u32 s5, s5, 0
	s_add_u32 s8, s8, 0x100
	s_addc_u32 s9, s9, 0
	s_cmp_ge_u32 s10, s83
	s_mov_b32 s6, s10
	s_cbranch_scc0 .LBB0_254
	v_readlane_b32 s4, v255, 46
	v_readlane_b32 s5, v255, 47
	s_and_b64 vcc, exec, s[4:5]
	s_cbranch_vccz .LBB0_257
	s_barrier
